# speedup vs baseline: 1.0077x; 1.0003x over previous
; __device__ __forceinline__ void finishSM(f32x16& p0, f32x16& p1, float alpha, float& l_reg, bf16x8& pa0, bf16x8& pa1, bf16x8& pa2, bf16x8& pa3) {
; #pragma unroll
;   for (int r = 0; r < 16; ++r) p1[r] = __builtin_amdgcn_exp2f(p1[r]);
;   float ps = 0;
; #pragma unroll
;   for (int r = 0; r < 16; ++r) ps += p0[r];
; #pragma unroll
;   for (int r = 0; r < 16; ++r) ps += p1[r];
;   { auto rr = __builtin_amdgcn_permlane32_swap(__float_as_uint(ps), __float_as_uint(ps), false, false);
;     ps = __uint_as_float(rr[0]) + __uint_as_float(rr[1]); }
;   l_reg = l_reg * alpha + ps;
;     ...
;   PK4(p0, 0, pa0); PK4(p0, 8, pa1); PK4(p1, 0, pa2); PK4(p1, 8, pa3);
; template <int BUFOFF>
; __device__ __forceinline__ void qkt_mla(f32x16& p0, f32x16& p1, const int* ka, const bf16x8* qr, const char* qlds) {
;   typedef __attribute__((address_space(3))) const bf16x8* lp;
;   p0 = f32x16{}; p1 = f32x16{};
; #pragma unroll
;   for (int d0 = 0; d0 < 12; ++d0) {
;     const int a = ka[d0 & 3] + (d0 >> 2) * 128 + BUFOFF;
;     const bf16x8 b0 = *(lp)(a), b1 = *(lp)(a + 12288);
;     bf16x8 qf;
;     qf = qr[d0];
;     p0 = __builtin_amdgcn_mfma_f32_32x32x16_bf16(b0, qf, p0, 0, 0, 0);
;     p1 = __builtin_amdgcn_mfma_f32_32x32x16_bf16(b1, qf, p1, 0, 0, 0);
;   }
; }
.LBB0_115:
	s_mov_b32 s55, s43
	s_mov_b32 s43, s52
	ds_read_b128 v[64:67], v169 offset:24576
	ds_read_b128 v[68:71], v169 offset:36864
	ds_read_b128 v[214:217], v190 offset:24576
	ds_read_b128 v[218:221], v190 offset:36864
	s_waitcnt lgkmcnt(0)
	v_mfma_f32_32x32x16_bf16 v[80:95], v[64:67], v[140:143], v[226:241]
	v_add_f32_e32 v144, v200, v145
	v_mfma_f32_32x32x16_bf16 v[64:79], v[68:71], v[140:143], v[226:241]
	v_add_f32_e32 v243, v203, v210
	v_add_f32_e32 v244, v202, v208
	v_add_f32_e32 v245, v205, v212
	v_add_f32_e32 v246, v199, v211
	v_add_f32_e32 v247, v201, v213
	v_mfma_f32_32x32x16_bf16 v[80:95], v[214:217], v[136:139], v[80:95]
	v_add_f32_e32 v251, v204, v207
	v_add_f32_e32 v252, v206, v209
	v_mov_b32_e32 v196, v158
	v_add_f32_e32 v144, v172, v144
	v_add_f32_e32 v243, v173, v243
	v_mfma_f32_32x32x16_bf16 v[64:79], v[218:221], v[136:139], v[64:79]
	ds_read_b128 v[214:217], v193 offset:24576
	ds_read_b128 v[218:221], v193 offset:36864
	v_add_f32_e32 v244, v170, v244
	v_add_f32_e32 v245, v171, v245
	v_add_f32_e32 v246, v196, v246
	v_mov_b32_e32 v222, v147
	v_mov_b32_e32 v223, v154
	v_mov_b32_e32 v224, v155
	s_waitcnt lgkmcnt(0)
	v_mfma_f32_32x32x16_bf16 v[80:95], v[214:217], v[132:135], v[80:95]
	v_mfma_f32_32x32x16_bf16 v[64:79], v[218:221], v[132:135], v[64:79]
	ds_read_b128 v[214:217], v192 offset:24576
	ds_read_b128 v[218:221], v192 offset:36864
	s_waitcnt lgkmcnt(0)
	v_mfma_f32_32x32x16_bf16 v[80:95], v[214:217], v[128:131], v[80:95]
	v_mfma_f32_32x32x16_bf16 v[64:79], v[218:221], v[128:131], v[64:79]
	ds_read_b128 v[214:217], v169 offset:24704
	ds_read_b128 v[218:221], v169 offset:36992
	s_waitcnt lgkmcnt(0)
	v_mfma_f32_32x32x16_bf16 v[80:95], v[214:217], v[124:127], v[80:95]
	v_mfma_f32_32x32x16_bf16 v[64:79], v[218:221], v[124:127], v[64:79]
	ds_read_b128 v[214:217], v190 offset:24704
	ds_read_b128 v[218:221], v190 offset:36992
	s_waitcnt lgkmcnt(0)
	v_mfma_f32_32x32x16_bf16 v[80:95], v[214:217], v[120:123], v[80:95]
	v_mfma_f32_32x32x16_bf16 v[64:79], v[218:221], v[120:123], v[64:79]
	ds_read_b128 v[214:217], v193 offset:24704
	ds_read_b128 v[218:221], v193 offset:36992
	s_waitcnt lgkmcnt(0)
	v_mfma_f32_32x32x16_bf16 v[80:95], v[214:217], v[116:119], v[80:95]
	v_mfma_f32_32x32x16_bf16 v[64:79], v[218:221], v[116:119], v[64:79]
	ds_read_b128 v[214:217], v192 offset:24704
	ds_read_b128 v[218:221], v192 offset:36992
	s_waitcnt lgkmcnt(0)
	v_mfma_f32_32x32x16_bf16 v[80:95], v[214:217], v[112:115], v[80:95]
	v_mfma_f32_32x32x16_bf16 v[64:79], v[218:221], v[112:115], v[64:79]
	ds_read_b128 v[214:217], v169 offset:24832
	ds_read_b128 v[218:221], v169 offset:37120
	s_waitcnt lgkmcnt(0)
	v_mfma_f32_32x32x16_bf16 v[80:95], v[214:217], v[108:111], v[80:95]
	v_mfma_f32_32x32x16_bf16 v[64:79], v[218:221], v[108:111], v[64:79]
	ds_read_b128 v[214:217], v190 offset:24832
	ds_read_b128 v[218:221], v190 offset:37120
	s_waitcnt lgkmcnt(0)
	v_mfma_f32_32x32x16_bf16 v[80:95], v[214:217], v[104:107], v[80:95]
	v_mfma_f32_32x32x16_bf16 v[64:79], v[218:221], v[104:107], v[64:79]
	ds_read_b128 v[214:217], v193 offset:24832
	ds_read_b128 v[218:221], v193 offset:37120
	s_waitcnt lgkmcnt(0)
	v_mfma_f32_32x32x16_bf16 v[80:95], v[214:217], v[100:103], v[80:95]
	v_mfma_f32_32x32x16_bf16 v[64:79], v[218:221], v[100:103], v[64:79]
	ds_read_b128 v[214:217], v192 offset:24832
	ds_read_b128 v[218:221], v192 offset:37120
	s_waitcnt lgkmcnt(0)
	v_mfma_f32_32x32x16_bf16 v[80:95], v[214:217], v[96:99], v[80:95]
	v_mov_b32_e32 v214, v159
	v_mov_b32_e32 v215, v152
	v_mov_b32_e32 v216, v153
	v_mov_b32_e32 v217, v150
	v_add_f32_e32 v247, v214, v247
	v_add_f32_e32 v251, v215, v251
	v_add_f32_e32 v252, v216, v252
	v_mfma_f32_32x32x16_bf16 v[64:79], v[218:221], v[96:99], v[64:79]
	v_mov_b32_e32 v218, v151
	v_mov_b32_e32 v219, v148
	v_mov_b32_e32 v220, v149
	v_mov_b32_e32 v221, v146
	v_add_f32_e32 v144, v217, v144
	v_add_f32_e32 v243, v218, v243
	v_add_f32_e32 v244, v219, v244
	v_add_f32_e32 v245, v220, v245
	v_add_f32_e32 v246, v221, v246
	v_add_f32_e32 v247, v222, v247
	v_add_f32_e32 v251, v223, v251
	v_add_f32_e32 v252, v224, v252
	v_add_f32_e32 v144, v144, v243
	v_add_f32_e32 v244, v244, v245
	v_add_f32_e32 v246, v246, v247
	v_add_f32_e32 v251, v251, v252
	v_add_f32_e32 v144, v144, v244
	v_add_f32_e32 v246, v246, v251
	v_add_f32_e32 v158, v144, v246
	v_mov_b32_e32 v159, v158
	v_cvt_pk_bf16_f32 v144, v145, v210
	v_cvt_pk_bf16_f32 v145, v208, v212
	v_cvt_pk_bf16_f32 v146, v211, v213
	v_cvt_pk_bf16_f32 v147, v207, v209
	v_cvt_pk_bf16_f32 v148, v200, v203
	v_cvt_pk_bf16_f32 v149, v202, v205
	v_cvt_pk_bf16_f32 v150, v199, v201
	v_cvt_pk_bf16_f32 v151, v204, v206
	v_cvt_pk_bf16_f32 v152, v172, v173
	v_cvt_pk_bf16_f32 v153, v170, v171
	v_cvt_pk_bf16_f32 v154, v196, v214
	s_nop 1
	v_permlane32_swap_b32_e32 v158, v159
	v_cvt_pk_bf16_f32 v155, v215, v216
	v_cvt_pk_bf16_f32 v170, v217, v218
	v_cvt_pk_bf16_f32 v171, v219, v220
	v_cvt_pk_bf16_f32 v172, v221, v222
	v_cvt_pk_bf16_f32 v173, v223, v224
	v_readlane_b32 s58, v249, 37
	v_readlane_b32 s59, v249, 38
	s_add_u32 s56, s58, s47
	s_addc_u32 s57, s59, s50
	s_add_u32 s4, s56, 0x17060000
	s_addc_u32 s5, s57, 0
	s_add_u32 s58, s58, s14
	s_addc_u32 s59, s59, s15
	s_add_u32 s60, s58, 0x1a040000
	s_mov_b32 m0, s41
	s_addc_u32 s61, s59, 0
	s_lshl_b32 s52, s54, 14
	s_add_i32 s62, s40, s52
	global_load_lds_dwordx4 v188, s[4:5]
	s_mov_b32 m0, s42
	s_nop 0
	global_load_lds_dwordx4 v189, s[4:5]
	s_add_i32 m0, s41, 0x4000
	s_nop 0
	global_load_lds_dwordx4 v191, s[4:5]
	s_mov_b32 m0, s62
	s_nop 0
	global_load_lds_dwordx4 v194, s[60:61]
	s_add_i32 m0, s62, 0x2000
	s_nop 0
	global_load_lds_dwordx4 v195, s[60:61]
	s_lshl_b32 s60, s43, 14
	v_add_u32_e32 v196, s60, v167
	ds_read_b64_tr_b16 v[200:201], v196 offset:0
	ds_read_b64_tr_b16 v[202:203], v196 offset:0x800
	ds_read_b64_tr_b16 v[204:205], v196 offset:0x1000
	ds_read_b64_tr_b16 v[206:207], v196 offset:0x1800
	ds_read_b64_tr_b16 v[208:209], v196 offset:0x2000
	ds_read_b64_tr_b16 v[210:211], v196 offset:0x2800
	ds_read_b64_tr_b16 v[212:213], v196 offset:0x3000
	ds_read_b64_tr_b16 v[214:215], v196 offset:0x3800
	s_nop 0
	s_waitcnt lgkmcnt(6)
; #define SBAR() __builtin_amdgcn_sched_barrier(0)
; template <int MLA>
; __device__ __forceinline__ void partialSM(f32x16& p0, f32x16& p1, float& m_reg, float& mn, float& alpha) {
;     ...
;   float pmax = p0[0];
; #pragma unroll
;   for (int r = 1; r < 16; ++r) pmax = fmaxf(pmax, p0[r]);
; #pragma unroll
;   for (int r = 0; r < 16; ++r) pmax = fmaxf(pmax, p1[r]);
;   { auto rr = __builtin_amdgcn_permlane32_swap(__float_as_uint(pmax), __float_as_uint(pmax), false, false);
;     pmax = fmaxf(__uint_as_float(rr[0]), __uint_as_float(rr[1])); }
;   if (__builtin_expect(__all(pmax - m_reg <= THR / SCALE), 1)) { mn = m_reg; alpha = 1.f; }
;   else { mn = fmaxf(m_reg, pmax); alpha = __builtin_amdgcn_exp2f((m_reg - mn) * C); m_reg = mn; }
; template <int D0> __device__ __forceinline__ void pv_one_t(f32x16& od, int vb, bf16x8 pa0, bf16x8 pa1, bf16x8 pa2, bf16x8 pa3) {
;   const s16x4 l0 = tr_read<v_rd_off(D0, 0, 0)>(vb), h0 = tr_read<v_rd_off(D0, 0, 1)>(vb), l1 = tr_read<v_rd_off(D0, 1, 0)>(vb), h1 = tr_read<v_rd_off(D0, 1, 1)>(vb);
;   const s16x4 l2 = tr_read<v_rd_off(D0, 2, 0)>(vb), h2 = tr_read<v_rd_off(D0, 2, 1)>(vb), l3 = tr_read<v_rd_off(D0, 3, 0)>(vb), h3 = tr_read<v_rd_off(D0, 3, 1)>(vb);
;   asm volatile("s_waitcnt lgkmcnt(0)" ::: "memory"); SBAR();
;     ...
;   od = __builtin_amdgcn_mfma_f32_32x32x16_bf16(PK(l0, h0), pa0, od, 0, 0, 0);
;   od = __builtin_amdgcn_mfma_f32_32x32x16_bf16(PK(l1, h1), pa1, od, 0, 0, 0);
;   od = __builtin_amdgcn_mfma_f32_32x32x16_bf16(PK(l2, h2), pa2, od, 0, 0, 0);
;   od = __builtin_amdgcn_mfma_f32_32x32x16_bf16(PK(l3, h3), pa3, od, 0, 0, 0);
;     ...
; }
	v_mfma_f32_32x32x16_bf16 v[0:15], v[200:203], v[144:147], v[0:15]
	ds_read_b64_tr_b16 v[200:201], v196 offset:0x200
	ds_read_b64_tr_b16 v[202:203], v196 offset:0xa00
	s_waitcnt lgkmcnt(6)
	v_mfma_f32_32x32x16_bf16 v[0:15], v[204:207], v[148:151], v[0:15]
	ds_read_b64_tr_b16 v[204:205], v196 offset:0x1200
	ds_read_b64_tr_b16 v[206:207], v196 offset:0x1a00
	s_waitcnt lgkmcnt(6)
	v_mfma_f32_32x32x16_bf16 v[0:15], v[208:211], v[152:155], v[0:15]
	ds_read_b64_tr_b16 v[208:209], v196 offset:0x2200
	ds_read_b64_tr_b16 v[210:211], v196 offset:0x2a00
	s_waitcnt lgkmcnt(6)
	v_mfma_f32_32x32x16_bf16 v[0:15], v[212:215], v[170:173], v[0:15]
	ds_read_b64_tr_b16 v[212:213], v196 offset:0x3200
	ds_read_b64_tr_b16 v[214:215], v196 offset:0x3a00
	s_waitcnt lgkmcnt(6)
	v_mfma_f32_32x32x16_bf16 v[48:63], v[200:203], v[144:147], v[48:63]
	ds_read_b64_tr_b16 v[200:201], v196 offset:0x400
	ds_read_b64_tr_b16 v[202:203], v196 offset:0xc00
	s_waitcnt lgkmcnt(6)
	v_mfma_f32_32x32x16_bf16 v[48:63], v[204:207], v[148:151], v[48:63]
	ds_read_b64_tr_b16 v[204:205], v196 offset:0x1400
	ds_read_b64_tr_b16 v[206:207], v196 offset:0x1c00
	s_waitcnt lgkmcnt(6)
	v_mfma_f32_32x32x16_bf16 v[48:63], v[208:211], v[152:155], v[48:63]
	ds_read_b64_tr_b16 v[208:209], v196 offset:0x2400
	ds_read_b64_tr_b16 v[210:211], v196 offset:0x2c00
	s_waitcnt lgkmcnt(6)
	v_mfma_f32_32x32x16_bf16 v[48:63], v[212:215], v[170:173], v[48:63]
	ds_read_b64_tr_b16 v[212:213], v196 offset:0x3400
	ds_read_b64_tr_b16 v[214:215], v196 offset:0x3c00
	s_waitcnt lgkmcnt(6)
	v_mfma_f32_32x32x16_bf16 v[32:47], v[200:203], v[144:147], v[32:47]
	ds_read_b64_tr_b16 v[200:201], v196 offset:0x600
	ds_read_b64_tr_b16 v[202:203], v196 offset:0xe00
	s_waitcnt lgkmcnt(6)
	v_mfma_f32_32x32x16_bf16 v[32:47], v[204:207], v[148:151], v[32:47]
	ds_read_b64_tr_b16 v[204:205], v196 offset:0x1600
	ds_read_b64_tr_b16 v[206:207], v196 offset:0x1e00
	s_waitcnt lgkmcnt(6)
	v_mfma_f32_32x32x16_bf16 v[32:47], v[208:211], v[152:155], v[32:47]
	ds_read_b64_tr_b16 v[208:209], v196 offset:0x2600
	ds_read_b64_tr_b16 v[210:211], v196 offset:0x2e00
	s_waitcnt lgkmcnt(6)
	v_mfma_f32_32x32x16_bf16 v[32:47], v[212:215], v[170:173], v[32:47]
	ds_read_b64_tr_b16 v[212:213], v196 offset:0x3600
	ds_read_b64_tr_b16 v[214:215], v196 offset:0x3e00
	s_waitcnt lgkmcnt(6)
	v_mfma_f32_32x32x16_bf16 v[16:31], v[200:203], v[144:147], v[16:31]
	v_max_f32_e32 v144, v80, v81
	v_max3_f32 v144, v144, v82, v83
	v_max3_f32 v144, v144, v84, v85
	v_max3_f32 v144, v144, v86, v87
	v_max3_f32 v144, v144, v88, v89
	v_max3_f32 v144, v144, v90, v91
	v_max3_f32 v144, v144, v92, v93
	s_waitcnt lgkmcnt(4)
	v_mfma_f32_32x32x16_bf16 v[16:31], v[204:207], v[148:151], v[16:31]
	v_max3_f32 v144, v144, v94, v95
	v_max3_f32 v144, v144, v64, v65
	v_max3_f32 v144, v144, v66, v67
	v_max3_f32 v144, v144, v68, v69
	v_max3_f32 v144, v144, v70, v71
	v_max3_f32 v144, v144, v72, v73
	v_max3_f32 v144, v144, v74, v75
	v_max3_f32 v144, v144, v76, v77
	s_waitcnt lgkmcnt(2)
	v_mfma_f32_32x32x16_bf16 v[16:31], v[208:211], v[152:155], v[16:31]
	v_max3_f32 v144, v144, v78, v79
	v_mov_b32_e32 v145, v144
	s_nop 1
	v_permlane32_swap_b32_e32 v144, v145
	v_max_f32_e32 v144, v144, v145
	v_cmp_ge_f32_e32 vcc, s63, v144
	s_waitcnt lgkmcnt(0)
	v_mfma_f32_32x32x16_bf16 v[16:31], v[212:215], v[170:173], v[16:31]
	s_cmp_eq_u64 vcc, exec
	s_cselect_b64 s[4:5], -1, 0
	s_waitcnt vmcnt(0) lgkmcnt(0)
	s_barrier
	s_cbranch_scc1 .Lal_c_m1
	v_max_f32_e32 v242, 0, v144
	v_exp_f32_e64 v152, -v242
	s_nop 0
	v_pk_mul_f32 v[14:15], v[14:15], v[152:153] op_sel_hi:[1,0]
	v_pk_mul_f32 v[12:13], v[12:13], v[152:153] op_sel_hi:[1,0]
	v_pk_mul_f32 v[10:11], v[10:11], v[152:153] op_sel_hi:[1,0]
	v_pk_mul_f32 v[8:9], v[8:9], v[152:153] op_sel_hi:[1,0]
	v_pk_mul_f32 v[6:7], v[6:7], v[152:153] op_sel_hi:[1,0]
	v_pk_mul_f32 v[4:5], v[4:5], v[152:153] op_sel_hi:[1,0]
	v_pk_mul_f32 v[2:3], v[2:3], v[152:153] op_sel_hi:[1,0]
	v_pk_mul_f32 v[0:1], v[0:1], v[152:153] op_sel_hi:[1,0]
	v_pk_mul_f32 v[62:63], v[62:63], v[152:153] op_sel_hi:[1,0]
	v_pk_mul_f32 v[60:61], v[60:61], v[152:153] op_sel_hi:[1,0]
	v_pk_mul_f32 v[58:59], v[58:59], v[152:153] op_sel_hi:[1,0]
	v_pk_mul_f32 v[56:57], v[56:57], v[152:153] op_sel_hi:[1,0]
	v_pk_mul_f32 v[54:55], v[54:55], v[152:153] op_sel_hi:[1,0]
	v_pk_mul_f32 v[52:53], v[52:53], v[152:153] op_sel_hi:[1,0]
	v_pk_mul_f32 v[50:51], v[50:51], v[152:153] op_sel_hi:[1,0]
	v_pk_mul_f32 v[48:49], v[48:49], v[152:153] op_sel_hi:[1,0]
	v_pk_mul_f32 v[46:47], v[46:47], v[152:153] op_sel_hi:[1,0]
	v_pk_mul_f32 v[44:45], v[44:45], v[152:153] op_sel_hi:[1,0]
	v_pk_mul_f32 v[42:43], v[42:43], v[152:153] op_sel_hi:[1,0]
	v_pk_mul_f32 v[40:41], v[40:41], v[152:153] op_sel_hi:[1,0]
	v_pk_mul_f32 v[38:39], v[38:39], v[152:153] op_sel_hi:[1,0]
	v_pk_mul_f32 v[36:37], v[36:37], v[152:153] op_sel_hi:[1,0]
	v_pk_mul_f32 v[34:35], v[34:35], v[152:153] op_sel_hi:[1,0]
	v_pk_mul_f32 v[32:33], v[32:33], v[152:153] op_sel_hi:[1,0]
	v_pk_mul_f32 v[30:31], v[30:31], v[152:153] op_sel_hi:[1,0]
	v_pk_mul_f32 v[28:29], v[28:29], v[152:153] op_sel_hi:[1,0]
	v_pk_mul_f32 v[26:27], v[26:27], v[152:153] op_sel_hi:[1,0]
	v_pk_mul_f32 v[24:25], v[24:25], v[152:153] op_sel_hi:[1,0]
	v_pk_mul_f32 v[22:23], v[22:23], v[152:153] op_sel_hi:[1,0]
	v_pk_mul_f32 v[20:21], v[20:21], v[152:153] op_sel_hi:[1,0]
	v_pk_mul_f32 v[18:19], v[18:19], v[152:153] op_sel_hi:[1,0]
	v_pk_mul_f32 v[16:17], v[16:17], v[152:153] op_sel_hi:[1,0]
	v_sub_f32_e32 v80, v80, v242
	v_sub_f32_e32 v81, v81, v242
	v_sub_f32_e32 v82, v82, v242
	v_sub_f32_e32 v83, v83, v242
	v_sub_f32_e32 v84, v84, v242
	v_sub_f32_e32 v85, v85, v242
	v_sub_f32_e32 v86, v86, v242
	v_sub_f32_e32 v87, v87, v242
	v_sub_f32_e32 v88, v88, v242
	v_sub_f32_e32 v89, v89, v242
	v_sub_f32_e32 v90, v90, v242
	v_sub_f32_e32 v91, v91, v242
	v_sub_f32_e32 v92, v92, v242
	v_sub_f32_e32 v93, v93, v242
	v_sub_f32_e32 v94, v94, v242
	v_sub_f32_e32 v95, v95, v242
	v_sub_f32_e32 v64, v64, v242
	v_sub_f32_e32 v65, v65, v242
	v_sub_f32_e32 v66, v66, v242
	v_sub_f32_e32 v67, v67, v242
	v_sub_f32_e32 v68, v68, v242
	v_sub_f32_e32 v69, v69, v242
	v_sub_f32_e32 v70, v70, v242
	v_sub_f32_e32 v71, v71, v242
	v_sub_f32_e32 v72, v72, v242
	v_sub_f32_e32 v73, v73, v242
	v_sub_f32_e32 v74, v74, v242
	v_sub_f32_e32 v75, v75, v242
	v_sub_f32_e32 v76, v76, v242
	v_sub_f32_e32 v77, v77, v242
	v_sub_f32_e32 v78, v78, v242
	v_sub_f32_e32 v79, v79, v242
	v_sub_f32_e32 v226, v226, v242
	v_sub_f32_e32 v227, v227, v242
	v_sub_f32_e32 v228, v228, v242
	v_sub_f32_e32 v229, v229, v242
	v_sub_f32_e32 v230, v230, v242
	v_sub_f32_e32 v231, v231, v242
	v_sub_f32_e32 v232, v232, v242
	v_sub_f32_e32 v233, v233, v242
	v_sub_f32_e32 v234, v234, v242
	v_sub_f32_e32 v235, v235, v242
	v_sub_f32_e32 v236, v236, v242
	v_sub_f32_e32 v237, v237, v242
	v_sub_f32_e32 v238, v238, v242
	v_sub_f32_e32 v239, v239, v242
	v_sub_f32_e32 v240, v240, v242
	v_sub_f32_e32 v241, v241, v242
	s_branch .LBB0_117

; template <int BUFOFF>
; __device__ __forceinline__ void qkt_mla(f32x16& p0, f32x16& p1, const int* ka, const bf16x8* qr, const char* qlds) {
;   typedef __attribute__((address_space(3))) const bf16x8* lp;
;   p0 = f32x16{}; p1 = f32x16{};
; #pragma unroll
;   for (int d0 = 0; d0 < 12; ++d0) {
;     const int a = ka[d0 & 3] + (d0 >> 2) * 128 + BUFOFF;
;     const bf16x8 b0 = *(lp)(a), b1 = *(lp)(a + 12288);
;     bf16x8 qf;
;     qf = qr[d0];
;     p0 = __builtin_amdgcn_mfma_f32_32x32x16_bf16(b0, qf, p0, 0, 0, 0);
;     p1 = __builtin_amdgcn_mfma_f32_32x32x16_bf16(b1, qf, p1, 0, 0, 0);
;   }
; }
.LBB0_117:
	v_exp_f32_e32 v155, v64
	v_exp_f32_e32 v170, v65
	v_exp_f32_e32 v171, v66
	v_exp_f32_e32 v172, v67
	v_exp_f32_e32 v173, v68
	v_exp_f32_e32 v197, v69
	v_exp_f32_e32 v199, v70
	v_exp_f32_e32 v200, v71
	v_exp_f32_e32 v201, v72
	v_exp_f32_e32 v202, v73
	v_exp_f32_e32 v203, v74
	v_exp_f32_e32 v204, v75
	v_exp_f32_e32 v205, v76
	v_exp_f32_e32 v222, v77
	v_exp_f32_e32 v223, v78
	v_exp_f32_e32 v154, v79
	v_exp_f32_e32 v206, v80
	v_exp_f32_e32 v207, v81
	v_exp_f32_e32 v208, v82
	v_exp_f32_e32 v209, v83
	v_exp_f32_e32 v210, v84
	v_exp_f32_e32 v211, v85
	v_exp_f32_e32 v212, v86
	v_exp_f32_e32 v213, v87
	v_exp_f32_e32 v214, v88
	v_exp_f32_e32 v215, v89
	v_exp_f32_e32 v216, v90
	v_exp_f32_e32 v217, v91
	v_exp_f32_e32 v218, v92
	v_exp_f32_e32 v219, v93
	v_exp_f32_e32 v220, v94
	v_exp_f32_e32 v221, v95
	ds_read_b128 v[64:67], v169
	ds_read_b128 v[68:71], v169 offset:12288
	ds_read_b128 v[144:147], v190
	ds_read_b128 v[148:151], v190 offset:12288
	v_mov_b32_e32 v224, v155
	s_waitcnt lgkmcnt(0)
	v_mfma_f32_32x32x16_bf16 v[80:95], v[64:67], v[140:143], v[226:241]
	v_mfma_f32_32x32x16_bf16 v[64:79], v[68:71], v[140:143], v[226:241]
	v_mov_b32_e32 v225, v154
	v_mfma_f32_32x32x16_bf16 v[80:95], v[144:147], v[136:139], v[80:95]
	v_mfma_f32_32x32x16_bf16 v[64:79], v[148:151], v[136:139], v[64:79]
	ds_read_b128 v[144:147], v193
	ds_read_b128 v[148:151], v193 offset:12288
	s_waitcnt lgkmcnt(0)
	v_mfma_f32_32x32x16_bf16 v[80:95], v[144:147], v[132:135], v[80:95]
	v_mfma_f32_32x32x16_bf16 v[64:79], v[148:151], v[132:135], v[64:79]
	ds_read_b128 v[144:147], v192
	ds_read_b128 v[148:151], v192 offset:12288
	s_waitcnt lgkmcnt(0)
	v_mfma_f32_32x32x16_bf16 v[80:95], v[144:147], v[128:131], v[80:95]
	v_mfma_f32_32x32x16_bf16 v[64:79], v[148:151], v[128:131], v[64:79]
	ds_read_b128 v[144:147], v169 offset:128
	ds_read_b128 v[148:151], v169 offset:12416
	s_waitcnt lgkmcnt(0)
	v_mfma_f32_32x32x16_bf16 v[80:95], v[144:147], v[124:127], v[80:95]
	v_mfma_f32_32x32x16_bf16 v[64:79], v[148:151], v[124:127], v[64:79]
	ds_read_b128 v[144:147], v190 offset:128
	ds_read_b128 v[148:151], v190 offset:12416
	s_waitcnt lgkmcnt(0)
	v_mfma_f32_32x32x16_bf16 v[80:95], v[144:147], v[120:123], v[80:95]
	v_mfma_f32_32x32x16_bf16 v[64:79], v[148:151], v[120:123], v[64:79]
	ds_read_b128 v[144:147], v193 offset:128
	ds_read_b128 v[148:151], v193 offset:12416
	s_waitcnt lgkmcnt(0)
	v_mfma_f32_32x32x16_bf16 v[80:95], v[144:147], v[116:119], v[80:95]
	v_mfma_f32_32x32x16_bf16 v[64:79], v[148:151], v[116:119], v[64:79]
	ds_read_b128 v[144:147], v192 offset:128
	ds_read_b128 v[148:151], v192 offset:12416
	s_waitcnt lgkmcnt(0)
	v_mfma_f32_32x32x16_bf16 v[80:95], v[144:147], v[112:115], v[80:95]
	v_mfma_f32_32x32x16_bf16 v[64:79], v[148:151], v[112:115], v[64:79]
	ds_read_b128 v[144:147], v169 offset:256
	ds_read_b128 v[148:151], v169 offset:12544
	s_waitcnt lgkmcnt(0)
	v_mfma_f32_32x32x16_bf16 v[80:95], v[144:147], v[108:111], v[80:95]
	v_mfma_f32_32x32x16_bf16 v[64:79], v[148:151], v[108:111], v[64:79]
	ds_read_b128 v[144:147], v190 offset:256
	ds_read_b128 v[148:151], v190 offset:12544
	s_waitcnt lgkmcnt(0)
	v_mfma_f32_32x32x16_bf16 v[80:95], v[144:147], v[104:107], v[80:95]
	v_mfma_f32_32x32x16_bf16 v[64:79], v[148:151], v[104:107], v[64:79]
	ds_read_b128 v[144:147], v193 offset:256
	ds_read_b128 v[148:151], v193 offset:12544
	s_waitcnt lgkmcnt(0)
	v_mfma_f32_32x32x16_bf16 v[80:95], v[144:147], v[100:103], v[80:95]
	v_mfma_f32_32x32x16_bf16 v[64:79], v[148:151], v[100:103], v[64:79]
	ds_read_b128 v[144:147], v192 offset:256
	ds_read_b128 v[148:151], v192 offset:12544
	s_waitcnt lgkmcnt(0)
	v_mfma_f32_32x32x16_bf16 v[80:95], v[144:147], v[96:99], v[80:95]
	v_add_f32_e32 v144, v214, v206
	v_add_f32_e32 v243, v215, v207
	v_add_f32_e32 v244, v216, v208
	v_add_f32_e32 v245, v217, v209
	v_add_f32_e32 v246, v218, v210
	v_add_f32_e32 v247, v219, v211
	v_add_f32_e32 v251, v220, v212
	v_add_f32_e32 v252, v221, v213
	v_add_f32_e32 v144, v224, v144
	v_add_f32_e32 v243, v170, v243
	v_add_f32_e32 v244, v171, v244
	v_add_f32_e32 v245, v172, v245
	v_add_f32_e32 v246, v173, v246
	v_add_f32_e32 v247, v197, v247
	v_add_f32_e32 v251, v199, v251
	v_add_f32_e32 v252, v200, v252
	v_add_f32_e32 v144, v201, v144
	v_add_f32_e32 v243, v202, v243
	v_mfma_f32_32x32x16_bf16 v[64:79], v[148:151], v[96:99], v[64:79]
	v_add_f32_e32 v244, v203, v244
	v_add_f32_e32 v245, v204, v245
	v_add_f32_e32 v246, v205, v246
	v_add_f32_e32 v247, v222, v247
	v_add_f32_e32 v251, v223, v251
	v_add_f32_e32 v252, v225, v252
	v_add_f32_e32 v144, v144, v243
	v_add_f32_e32 v244, v244, v245
	v_add_f32_e32 v246, v246, v247
	v_add_f32_e32 v251, v251, v252
	v_add_f32_e32 v144, v144, v244
	v_add_f32_e32 v246, v246, v251
	v_add_f32_e32 v154, v144, v246
	v_mov_b32_e32 v155, v154
	v_cvt_pk_bf16_f32 v144, v206, v207
	v_cvt_pk_bf16_f32 v145, v208, v209
	v_cvt_pk_bf16_f32 v146, v210, v211
	v_cvt_pk_bf16_f32 v147, v212, v213
	s_nop 1
	v_permlane32_swap_b32_e32 v154, v155
	v_cvt_pk_bf16_f32 v148, v214, v215
	v_cvt_pk_bf16_f32 v149, v216, v217
	v_cvt_pk_bf16_f32 v150, v218, v219
	v_cvt_pk_bf16_f32 v151, v220, v221
	v_cvt_pk_bf16_f32 v170, v224, v170
	v_cvt_pk_bf16_f32 v171, v171, v172
	v_cvt_pk_bf16_f32 v172, v173, v197
	v_cvt_pk_bf16_f32 v173, v199, v200
	v_cvt_pk_bf16_f32 v200, v201, v202
	v_cvt_pk_bf16_f32 v201, v203, v204
	v_cvt_pk_bf16_f32 v202, v205, v222
	v_cvt_pk_bf16_f32 v203, v223, v225
	s_nop 0
	s_add_u32 s4, s56, 0x17090000
	s_addc_u32 s5, s57, 0
	s_add_u32 s56, s58, 0x1a060000
	s_mov_b32 m0, s16
	s_addc_u32 s57, s59, 0
	s_add_i32 s58, s40, s60
	global_load_lds_dwordx4 v188, s[4:5]
	s_mov_b32 m0, s17
	s_nop 0
	global_load_lds_dwordx4 v189, s[4:5]
	s_mov_b32 m0, s44
	s_nop 0
	global_load_lds_dwordx4 v191, s[4:5]
	s_mov_b32 m0, s58
	s_nop 0
	global_load_lds_dwordx4 v194, s[56:57]
	s_add_i32 m0, s58, 0x2000
	s_nop 0
	global_load_lds_dwordx4 v195, s[56:57]
	v_lshl_add_u32 v197, s55, 14, v167
	ds_read_b64_tr_b16 v[204:205], v197 offset:0
	ds_read_b64_tr_b16 v[206:207], v197 offset:0x800
	ds_read_b64_tr_b16 v[208:209], v197 offset:0x1000
	ds_read_b64_tr_b16 v[210:211], v197 offset:0x1800
	ds_read_b64_tr_b16 v[212:213], v197 offset:0x2000
	ds_read_b64_tr_b16 v[214:215], v197 offset:0x2800
	ds_read_b64_tr_b16 v[216:217], v197 offset:0x3000
	ds_read_b64_tr_b16 v[218:219], v197 offset:0x3800
	s_nop 0
	s_waitcnt lgkmcnt(6)
; #define SBAR() __builtin_amdgcn_sched_barrier(0)
; template <int MLA>
; __device__ __forceinline__ void partialSM(f32x16& p0, f32x16& p1, float& m_reg, float& mn, float& alpha) {
;     ...
;   float pmax = p0[0];
; #pragma unroll
;   for (int r = 1; r < 16; ++r) pmax = fmaxf(pmax, p0[r]);
; #pragma unroll
;   for (int r = 0; r < 16; ++r) pmax = fmaxf(pmax, p1[r]);
;   { auto rr = __builtin_amdgcn_permlane32_swap(__float_as_uint(pmax), __float_as_uint(pmax), false, false);
;     pmax = fmaxf(__uint_as_float(rr[0]), __uint_as_float(rr[1])); }
;   if (__builtin_expect(__all(pmax - m_reg <= THR / SCALE), 1)) { mn = m_reg; alpha = 1.f; }
;   else { mn = fmaxf(m_reg, pmax); alpha = __builtin_amdgcn_exp2f((m_reg - mn) * C); m_reg = mn; }
; template <int D0> __device__ __forceinline__ void pv_one_t(f32x16& od, int vb, bf16x8 pa0, bf16x8 pa1, bf16x8 pa2, bf16x8 pa3) {
;   const s16x4 l0 = tr_read<v_rd_off(D0, 0, 0)>(vb), h0 = tr_read<v_rd_off(D0, 0, 1)>(vb), l1 = tr_read<v_rd_off(D0, 1, 0)>(vb), h1 = tr_read<v_rd_off(D0, 1, 1)>(vb);
;   const s16x4 l2 = tr_read<v_rd_off(D0, 2, 0)>(vb), h2 = tr_read<v_rd_off(D0, 2, 1)>(vb), l3 = tr_read<v_rd_off(D0, 3, 0)>(vb), h3 = tr_read<v_rd_off(D0, 3, 1)>(vb);
;   asm volatile("s_waitcnt lgkmcnt(0)" ::: "memory"); SBAR();
;     ...
;   od = __builtin_amdgcn_mfma_f32_32x32x16_bf16(PK(l0, h0), pa0, od, 0, 0, 0);
;   od = __builtin_amdgcn_mfma_f32_32x32x16_bf16(PK(l1, h1), pa1, od, 0, 0, 0);
;   od = __builtin_amdgcn_mfma_f32_32x32x16_bf16(PK(l2, h2), pa2, od, 0, 0, 0);
;   od = __builtin_amdgcn_mfma_f32_32x32x16_bf16(PK(l3, h3), pa3, od, 0, 0, 0);
;     ...
; }
	v_mfma_f32_32x32x16_bf16 v[0:15], v[204:207], v[144:147], v[0:15]
	ds_read_b64_tr_b16 v[204:205], v197 offset:0x200
	ds_read_b64_tr_b16 v[206:207], v197 offset:0xa00
	s_waitcnt lgkmcnt(6)
	v_mfma_f32_32x32x16_bf16 v[0:15], v[208:211], v[148:151], v[0:15]
	ds_read_b64_tr_b16 v[208:209], v197 offset:0x1200
	ds_read_b64_tr_b16 v[210:211], v197 offset:0x1a00
	s_waitcnt lgkmcnt(6)
	v_mfma_f32_32x32x16_bf16 v[0:15], v[212:215], v[170:173], v[0:15]
	ds_read_b64_tr_b16 v[212:213], v197 offset:0x2200
	ds_read_b64_tr_b16 v[214:215], v197 offset:0x2a00
	s_waitcnt lgkmcnt(6)
	v_mfma_f32_32x32x16_bf16 v[0:15], v[216:219], v[200:203], v[0:15]
	ds_read_b64_tr_b16 v[216:217], v197 offset:0x3200
	ds_read_b64_tr_b16 v[218:219], v197 offset:0x3a00
	s_waitcnt lgkmcnt(6)
	v_mfma_f32_32x32x16_bf16 v[48:63], v[204:207], v[144:147], v[48:63]
	ds_read_b64_tr_b16 v[204:205], v197 offset:0x400
	ds_read_b64_tr_b16 v[206:207], v197 offset:0xc00
	s_waitcnt lgkmcnt(6)
	v_mfma_f32_32x32x16_bf16 v[48:63], v[208:211], v[148:151], v[48:63]
	ds_read_b64_tr_b16 v[208:209], v197 offset:0x1400
	ds_read_b64_tr_b16 v[210:211], v197 offset:0x1c00
	s_waitcnt lgkmcnt(6)
	v_mfma_f32_32x32x16_bf16 v[48:63], v[212:215], v[170:173], v[48:63]
	ds_read_b64_tr_b16 v[212:213], v197 offset:0x2400
	ds_read_b64_tr_b16 v[214:215], v197 offset:0x2c00
	s_waitcnt lgkmcnt(6)
	v_mfma_f32_32x32x16_bf16 v[48:63], v[216:219], v[200:203], v[48:63]
	ds_read_b64_tr_b16 v[216:217], v197 offset:0x3400
	ds_read_b64_tr_b16 v[218:219], v197 offset:0x3c00
	s_waitcnt lgkmcnt(6)
	v_mfma_f32_32x32x16_bf16 v[32:47], v[204:207], v[144:147], v[32:47]
	ds_read_b64_tr_b16 v[204:205], v197 offset:0x600
	ds_read_b64_tr_b16 v[206:207], v197 offset:0xe00
	s_waitcnt lgkmcnt(6)
	v_mfma_f32_32x32x16_bf16 v[32:47], v[208:211], v[148:151], v[32:47]
	ds_read_b64_tr_b16 v[208:209], v197 offset:0x1600
	ds_read_b64_tr_b16 v[210:211], v197 offset:0x1e00
	s_waitcnt lgkmcnt(6)
	v_mfma_f32_32x32x16_bf16 v[32:47], v[212:215], v[170:173], v[32:47]
	ds_read_b64_tr_b16 v[212:213], v197 offset:0x2600
	ds_read_b64_tr_b16 v[214:215], v197 offset:0x2e00
	s_waitcnt lgkmcnt(6)
	v_mfma_f32_32x32x16_bf16 v[32:47], v[216:219], v[200:203], v[32:47]
	ds_read_b64_tr_b16 v[216:217], v197 offset:0x3600
	ds_read_b64_tr_b16 v[218:219], v197 offset:0x3e00
	s_waitcnt lgkmcnt(6)
	v_mfma_f32_32x32x16_bf16 v[16:31], v[204:207], v[144:147], v[16:31]
	v_max_f32_e32 v144, v80, v81
	v_max3_f32 v144, v144, v82, v83
	v_max3_f32 v144, v144, v84, v85
	v_max3_f32 v144, v144, v86, v87
	v_max3_f32 v144, v144, v88, v89
	v_max3_f32 v144, v144, v90, v91
	v_max3_f32 v144, v144, v92, v93
	s_waitcnt lgkmcnt(4)
	v_mfma_f32_32x32x16_bf16 v[16:31], v[208:211], v[148:151], v[16:31]
	v_max3_f32 v144, v144, v94, v95
	v_max3_f32 v144, v144, v64, v65
	v_max3_f32 v144, v144, v66, v67
	v_max3_f32 v144, v144, v68, v69
	v_max3_f32 v144, v144, v70, v71
	v_max3_f32 v144, v144, v72, v73
	v_max3_f32 v144, v144, v74, v75
	v_max3_f32 v144, v144, v76, v77
	s_waitcnt lgkmcnt(2)
	v_mfma_f32_32x32x16_bf16 v[16:31], v[212:215], v[170:173], v[16:31]
	v_max3_f32 v144, v144, v78, v79
	v_mov_b32_e32 v145, v144
	s_nop 1
	v_permlane32_swap_b32_e32 v144, v145
	v_max_f32_e32 v144, v144, v145
	v_cmp_ge_f32_e32 vcc, s63, v144
	s_waitcnt lgkmcnt(0)
	v_mfma_f32_32x32x16_bf16 v[16:31], v[216:219], v[200:203], v[16:31]
	s_cmp_eq_u64 vcc, exec
	s_cselect_b64 s[4:5], -1, 0
	s_waitcnt vmcnt(0) lgkmcnt(0)
	s_barrier
	s_cbranch_scc1 .Lal_c_m2
	v_max_f32_e32 v242, 0, v144
	v_exp_f32_e64 v144, -v242
	s_nop 0
	v_pk_mul_f32 v[14:15], v[14:15], v[144:145] op_sel_hi:[1,0]
	v_pk_mul_f32 v[12:13], v[12:13], v[144:145] op_sel_hi:[1,0]
	v_pk_mul_f32 v[10:11], v[10:11], v[144:145] op_sel_hi:[1,0]
	v_pk_mul_f32 v[8:9], v[8:9], v[144:145] op_sel_hi:[1,0]
	v_pk_mul_f32 v[6:7], v[6:7], v[144:145] op_sel_hi:[1,0]
	v_pk_mul_f32 v[4:5], v[4:5], v[144:145] op_sel_hi:[1,0]
	v_pk_mul_f32 v[2:3], v[2:3], v[144:145] op_sel_hi:[1,0]
	v_pk_mul_f32 v[0:1], v[0:1], v[144:145] op_sel_hi:[1,0]
	v_pk_mul_f32 v[62:63], v[62:63], v[144:145] op_sel_hi:[1,0]
	v_pk_mul_f32 v[60:61], v[60:61], v[144:145] op_sel_hi:[1,0]
	v_pk_mul_f32 v[58:59], v[58:59], v[144:145] op_sel_hi:[1,0]
	v_pk_mul_f32 v[56:57], v[56:57], v[144:145] op_sel_hi:[1,0]
	v_pk_mul_f32 v[54:55], v[54:55], v[144:145] op_sel_hi:[1,0]
	v_pk_mul_f32 v[52:53], v[52:53], v[144:145] op_sel_hi:[1,0]
	v_pk_mul_f32 v[50:51], v[50:51], v[144:145] op_sel_hi:[1,0]
	v_pk_mul_f32 v[48:49], v[48:49], v[144:145] op_sel_hi:[1,0]
	v_pk_mul_f32 v[46:47], v[46:47], v[144:145] op_sel_hi:[1,0]
	v_pk_mul_f32 v[44:45], v[44:45], v[144:145] op_sel_hi:[1,0]
	v_pk_mul_f32 v[42:43], v[42:43], v[144:145] op_sel_hi:[1,0]
	v_pk_mul_f32 v[40:41], v[40:41], v[144:145] op_sel_hi:[1,0]
	v_pk_mul_f32 v[38:39], v[38:39], v[144:145] op_sel_hi:[1,0]
	v_pk_mul_f32 v[36:37], v[36:37], v[144:145] op_sel_hi:[1,0]
	v_pk_mul_f32 v[34:35], v[34:35], v[144:145] op_sel_hi:[1,0]
	v_pk_mul_f32 v[32:33], v[32:33], v[144:145] op_sel_hi:[1,0]
	v_pk_mul_f32 v[30:31], v[30:31], v[144:145] op_sel_hi:[1,0]
	v_pk_mul_f32 v[28:29], v[28:29], v[144:145] op_sel_hi:[1,0]
	v_pk_mul_f32 v[26:27], v[26:27], v[144:145] op_sel_hi:[1,0]
	v_pk_mul_f32 v[24:25], v[24:25], v[144:145] op_sel_hi:[1,0]
	v_pk_mul_f32 v[22:23], v[22:23], v[144:145] op_sel_hi:[1,0]
	v_pk_mul_f32 v[20:21], v[20:21], v[144:145] op_sel_hi:[1,0]
	v_pk_mul_f32 v[18:19], v[18:19], v[144:145] op_sel_hi:[1,0]
	v_pk_mul_f32 v[16:17], v[16:17], v[144:145] op_sel_hi:[1,0]
	v_sub_f32_e32 v80, v80, v242
	v_sub_f32_e32 v81, v81, v242
	v_sub_f32_e32 v82, v82, v242
	v_sub_f32_e32 v83, v83, v242
	v_sub_f32_e32 v84, v84, v242
	v_sub_f32_e32 v85, v85, v242
	v_sub_f32_e32 v86, v86, v242
	v_sub_f32_e32 v87, v87, v242
	v_sub_f32_e32 v88, v88, v242
	v_sub_f32_e32 v89, v89, v242
	v_sub_f32_e32 v90, v90, v242
	v_sub_f32_e32 v91, v91, v242
	v_sub_f32_e32 v92, v92, v242
	v_sub_f32_e32 v93, v93, v242
	v_sub_f32_e32 v94, v94, v242
	v_sub_f32_e32 v95, v95, v242
	v_sub_f32_e32 v64, v64, v242
	v_sub_f32_e32 v65, v65, v242
	v_sub_f32_e32 v66, v66, v242
	v_sub_f32_e32 v67, v67, v242
	v_sub_f32_e32 v68, v68, v242
	v_sub_f32_e32 v69, v69, v242
	v_sub_f32_e32 v70, v70, v242
	v_sub_f32_e32 v71, v71, v242
	v_sub_f32_e32 v72, v72, v242
	v_sub_f32_e32 v73, v73, v242
	v_sub_f32_e32 v74, v74, v242
	v_sub_f32_e32 v75, v75, v242
	v_sub_f32_e32 v76, v76, v242
	v_sub_f32_e32 v77, v77, v242
	v_sub_f32_e32 v78, v78, v242
	v_sub_f32_e32 v79, v79, v242
	v_sub_f32_e32 v226, v226, v242
	v_sub_f32_e32 v227, v227, v242
	v_sub_f32_e32 v228, v228, v242
	v_sub_f32_e32 v229, v229, v242
	v_sub_f32_e32 v230, v230, v242
	v_sub_f32_e32 v231, v231, v242
	v_sub_f32_e32 v232, v232, v242
	v_sub_f32_e32 v233, v233, v242
	v_sub_f32_e32 v234, v234, v242
	v_sub_f32_e32 v235, v235, v242
	v_sub_f32_e32 v236, v236, v242
	v_sub_f32_e32 v237, v237, v242
	v_sub_f32_e32 v238, v238, v242
	v_sub_f32_e32 v239, v239, v242
	v_sub_f32_e32 v240, v240, v242
	v_sub_f32_e32 v241, v241, v242
	s_branch .LBB0_119

; __device__ __forceinline__ void finishSM(f32x16& p0, f32x16& p1, float alpha, float& l_reg, bf16x8& pa0, bf16x8& pa1, bf16x8& pa2, bf16x8& pa3) {
; #pragma unroll
;   for (int r = 0; r < 16; ++r) p1[r] = __builtin_amdgcn_exp2f(p1[r]);
;   float ps = 0;
; #pragma unroll
;   for (int r = 0; r < 16; ++r) ps += p0[r];
; #pragma unroll
;   for (int r = 0; r < 16; ++r) ps += p1[r];
;   { auto rr = __builtin_amdgcn_permlane32_swap(__float_as_uint(ps), __float_as_uint(ps), false, false);
;     ps = __uint_as_float(rr[0]) + __uint_as_float(rr[1]); }
;   l_reg = l_reg * alpha + ps;
;     ...
;   PK4(p0, 0, pa0); PK4(p0, 8, pa1); PK4(p1, 0, pa2); PK4(p1, 8, pa3);
; template <int BUFOFF>
; __device__ __forceinline__ void qkt_diff(f32x16& p0, f32x16& p1, const int* ka, const bf16x8* qr) {
;   typedef __attribute__((address_space(3))) const bf16x8* lp;
;   p0 = f32x16{}; p1 = f32x16{};
; #pragma unroll
;   for (int d0 = 0; d0 < 4; ++d0) {
;     const int a = ka[d0] + BUFOFF;
;     const bf16x8 b0 = *(lp)(a), b1 = *(lp)(a + 8192);
;     p0 = __builtin_amdgcn_mfma_f32_32x32x16_bf16(b0, qr[d0], p0, 0, 0, 0);
;     p1 = __builtin_amdgcn_mfma_f32_32x32x16_bf16(b1, qr[d0], p1, 0, 0, 0);
;   }
; }
.LBB0_129:
	s_mov_b32 s54, s47
	s_mov_b32 s47, s52
	ds_read_b128 v[64:67], v138 offset:16384
	ds_read_b128 v[68:71], v138 offset:24576
	ds_read_b128 v[170:173], v141 offset:16384
	ds_read_b128 v[188:191], v141 offset:24576
	s_waitcnt lgkmcnt(0)
	v_mfma_f32_32x32x16_bf16 v[80:95], v[64:67], v[108:111], v[226:241]
	v_add_f32_e32 v112, v144, v113
	v_mfma_f32_32x32x16_bf16 v[64:79], v[68:71], v[108:111], v[226:241]
	v_add_f32_e32 v243, v148, v155
	v_add_f32_e32 v244, v145, v152
	v_add_f32_e32 v245, v149, v156
	v_add_f32_e32 v246, v146, v153
	v_add_f32_e32 v247, v150, v158
	v_mfma_f32_32x32x16_bf16 v[80:95], v[170:173], v[104:107], v[80:95]
	v_add_f32_e32 v251, v147, v154
	v_add_f32_e32 v252, v151, v159
	v_mov_b32_e32 v132, v124
	v_add_f32_e32 v112, v128, v112
	v_mov_b32_e32 v162, v125
	v_mfma_f32_32x32x16_bf16 v[64:79], v[188:191], v[104:107], v[64:79]
	ds_read_b128 v[170:173], v140 offset:16384
	ds_read_b128 v[188:191], v140 offset:24576
	v_add_f32_e32 v243, v129, v243
	v_mov_b32_e32 v167, v120
	v_add_f32_e32 v244, v126, v244
	v_mov_b32_e32 v169, v121
	v_add_f32_e32 v245, v127, v245
	v_add_f32_e32 v246, v132, v246
	s_waitcnt lgkmcnt(0)
	v_mfma_f32_32x32x16_bf16 v[80:95], v[170:173], v[100:103], v[80:95]
	v_add_f32_e32 v247, v162, v247
	v_add_f32_e32 v251, v167, v251
	v_add_f32_e32 v252, v169, v252
	v_mfma_f32_32x32x16_bf16 v[64:79], v[188:191], v[100:103], v[64:79]
	ds_read_b128 v[170:173], v139 offset:16384
	ds_read_b128 v[188:191], v139 offset:24576
	s_waitcnt lgkmcnt(0)
	v_mfma_f32_32x32x16_bf16 v[80:95], v[170:173], v[96:99], v[80:95]
	v_mov_b32_e32 v170, v118
	v_mov_b32_e32 v171, v117
	v_mov_b32_e32 v172, v114
	v_mov_b32_e32 v173, v115
	v_add_f32_e32 v112, v170, v112
	v_add_f32_e32 v243, v119, v243
	v_add_f32_e32 v244, v116, v244
	v_mfma_f32_32x32x16_bf16 v[64:79], v[188:191], v[96:99], v[64:79]
	v_mov_b32_e32 v188, v122
	v_mov_b32_e32 v189, v123
	v_add_f32_e32 v245, v171, v245
	v_add_f32_e32 v246, v172, v246
	v_add_f32_e32 v247, v173, v247
	v_add_f32_e32 v251, v188, v251
	v_add_f32_e32 v252, v189, v252
	v_add_f32_e32 v112, v112, v243
	v_add_f32_e32 v244, v244, v245
	v_add_f32_e32 v246, v246, v247
	v_add_f32_e32 v251, v251, v252
	v_add_f32_e32 v112, v112, v244
	v_add_f32_e32 v246, v246, v251
	v_add_f32_e32 v117, v112, v246
	v_mov_b32_e32 v118, v117
	v_cvt_pk_bf16_f32 v112, v113, v155
	v_cvt_pk_bf16_f32 v113, v152, v156
	v_cvt_pk_bf16_f32 v114, v153, v158
	s_nop 1
	v_permlane32_swap_b32_e32 v117, v118
	v_cvt_pk_bf16_f32 v115, v154, v159
	v_cvt_pk_bf16_f32 v120, v144, v148
	v_cvt_pk_bf16_f32 v121, v145, v149
	v_cvt_pk_bf16_f32 v122, v146, v150
	v_cvt_pk_bf16_f32 v123, v147, v151
	v_cvt_pk_bf16_f32 v124, v128, v129
	v_cvt_pk_bf16_f32 v125, v126, v127
	v_cvt_pk_bf16_f32 v126, v132, v162
	v_cvt_pk_bf16_f32 v127, v167, v169
	v_cvt_pk_bf16_f32 v144, v170, v119
	v_cvt_pk_bf16_f32 v145, v116, v171
	v_cvt_pk_bf16_f32 v146, v172, v173
	v_cvt_pk_bf16_f32 v147, v188, v189
	s_add_u32 s4, s14, 0x2000000
	s_mov_b32 m0, s43
	s_addc_u32 s5, s15, 0
	s_mov_b64 s[56:57], s[14:15]
	s_lshl_b32 s52, s53, 14
	s_add_i32 s55, s42, s52
	s_nop 0
	global_load_lds_dwordx4 v134, s[56:57]
	s_mov_b32 m0, s44
	s_nop 0
	global_load_lds_dwordx4 v135, s[56:57]
	s_mov_b32 m0, s55
	s_nop 0
	global_load_lds_dwordx4 v136, s[4:5]
	s_add_i32 m0, s55, 0x2000
	s_nop 0
	global_load_lds_dwordx4 v137, s[4:5]
	s_lshl_b32 s55, s47, 14
	v_add_u32_e32 v132, s55, v133
	ds_read_b64_tr_b16 v[148:149], v132 offset:0
	ds_read_b64_tr_b16 v[150:151], v132 offset:0x800
	ds_read_b64_tr_b16 v[152:153], v132 offset:0x1000
	ds_read_b64_tr_b16 v[154:155], v132 offset:0x1800
	ds_read_b64_tr_b16 v[170:171], v132 offset:0x2000
	ds_read_b64_tr_b16 v[172:173], v132 offset:0x2800
	ds_read_b64_tr_b16 v[188:189], v132 offset:0x3000
	ds_read_b64_tr_b16 v[190:191], v132 offset:0x3800
	s_nop 0
	s_waitcnt lgkmcnt(6)
	v_mfma_f32_32x32x16_bf16 v[32:47], v[148:151], v[112:115], v[32:47]
	ds_read_b64_tr_b16 v[148:149], v132 offset:0x200
	ds_read_b64_tr_b16 v[150:151], v132 offset:0xa00
	s_waitcnt lgkmcnt(6)
	v_mfma_f32_32x32x16_bf16 v[32:47], v[152:155], v[120:123], v[32:47]
	ds_read_b64_tr_b16 v[152:153], v132 offset:0x1200
	ds_read_b64_tr_b16 v[154:155], v132 offset:0x1a00
	s_waitcnt lgkmcnt(6)
	v_mfma_f32_32x32x16_bf16 v[32:47], v[170:173], v[124:127], v[32:47]
	ds_read_b64_tr_b16 v[170:171], v132 offset:0x2200
	ds_read_b64_tr_b16 v[172:173], v132 offset:0x2a00
	s_waitcnt lgkmcnt(6)
	v_mfma_f32_32x32x16_bf16 v[32:47], v[188:191], v[144:147], v[32:47]
	ds_read_b64_tr_b16 v[188:189], v132 offset:0x3200
	ds_read_b64_tr_b16 v[190:191], v132 offset:0x3a00
	s_waitcnt lgkmcnt(6)
	v_mfma_f32_32x32x16_bf16 v[48:63], v[148:151], v[112:115], v[48:63]
	ds_read_b64_tr_b16 v[148:149], v132 offset:0x400
	ds_read_b64_tr_b16 v[150:151], v132 offset:0xc00
	s_waitcnt lgkmcnt(6)
	v_mfma_f32_32x32x16_bf16 v[48:63], v[152:155], v[120:123], v[48:63]
	ds_read_b64_tr_b16 v[152:153], v132 offset:0x1400
	ds_read_b64_tr_b16 v[154:155], v132 offset:0x1c00
	s_waitcnt lgkmcnt(6)
	v_mfma_f32_32x32x16_bf16 v[48:63], v[170:173], v[124:127], v[48:63]
	ds_read_b64_tr_b16 v[170:171], v132 offset:0x2400
	ds_read_b64_tr_b16 v[172:173], v132 offset:0x2c00
	s_waitcnt lgkmcnt(6)
	v_mfma_f32_32x32x16_bf16 v[48:63], v[188:191], v[144:147], v[48:63]
	ds_read_b64_tr_b16 v[188:189], v132 offset:0x3400
	ds_read_b64_tr_b16 v[190:191], v132 offset:0x3c00
	s_waitcnt lgkmcnt(6)
; #define SBAR() __builtin_amdgcn_sched_barrier(0)
; template <int MLA>
; __device__ __forceinline__ void partialSM(f32x16& p0, f32x16& p1, float& m_reg, float& mn, float& alpha) {
;     ...
;   float pmax = p0[0];
; #pragma unroll
;   for (int r = 1; r < 16; ++r) pmax = fmaxf(pmax, p0[r]);
; #pragma unroll
;   for (int r = 0; r < 16; ++r) pmax = fmaxf(pmax, p1[r]);
;   { auto rr = __builtin_amdgcn_permlane32_swap(__float_as_uint(pmax), __float_as_uint(pmax), false, false);
;     pmax = fmaxf(__uint_as_float(rr[0]), __uint_as_float(rr[1])); }
;   if (__builtin_expect(__all(pmax - m_reg <= THR / SCALE), 1)) { mn = m_reg; alpha = 1.f; }
;   else { mn = fmaxf(m_reg, pmax); alpha = __builtin_amdgcn_exp2f((m_reg - mn) * C); m_reg = mn; }
; template <int D0> __device__ __forceinline__ void pv_one_t(f32x16& od, int vb, bf16x8 pa0, bf16x8 pa1, bf16x8 pa2, bf16x8 pa3) {
;   const s16x4 l0 = tr_read<v_rd_off(D0, 0, 0)>(vb), h0 = tr_read<v_rd_off(D0, 0, 1)>(vb), l1 = tr_read<v_rd_off(D0, 1, 0)>(vb), h1 = tr_read<v_rd_off(D0, 1, 1)>(vb);
;   const s16x4 l2 = tr_read<v_rd_off(D0, 2, 0)>(vb), h2 = tr_read<v_rd_off(D0, 2, 1)>(vb), l3 = tr_read<v_rd_off(D0, 3, 0)>(vb), h3 = tr_read<v_rd_off(D0, 3, 1)>(vb);
;   asm volatile("s_waitcnt lgkmcnt(0)" ::: "memory"); SBAR();
;     ...
;   od = __builtin_amdgcn_mfma_f32_32x32x16_bf16(PK(l0, h0), pa0, od, 0, 0, 0);
;   od = __builtin_amdgcn_mfma_f32_32x32x16_bf16(PK(l1, h1), pa1, od, 0, 0, 0);
;   od = __builtin_amdgcn_mfma_f32_32x32x16_bf16(PK(l2, h2), pa2, od, 0, 0, 0);
;   od = __builtin_amdgcn_mfma_f32_32x32x16_bf16(PK(l3, h3), pa3, od, 0, 0, 0);
;     ...
; }
	v_mfma_f32_32x32x16_bf16 v[16:31], v[148:151], v[112:115], v[16:31]
	ds_read_b64_tr_b16 v[148:149], v132 offset:0x600
	ds_read_b64_tr_b16 v[150:151], v132 offset:0xe00
	s_waitcnt lgkmcnt(6)
	v_mfma_f32_32x32x16_bf16 v[16:31], v[152:155], v[120:123], v[16:31]
	ds_read_b64_tr_b16 v[152:153], v132 offset:0x1600
	ds_read_b64_tr_b16 v[154:155], v132 offset:0x1e00
	s_waitcnt lgkmcnt(6)
	v_mfma_f32_32x32x16_bf16 v[16:31], v[170:173], v[124:127], v[16:31]
	ds_read_b64_tr_b16 v[170:171], v132 offset:0x2600
	ds_read_b64_tr_b16 v[172:173], v132 offset:0x2e00
	s_waitcnt lgkmcnt(6)
	v_mfma_f32_32x32x16_bf16 v[16:31], v[188:191], v[144:147], v[16:31]
	ds_read_b64_tr_b16 v[188:189], v132 offset:0x3600
	ds_read_b64_tr_b16 v[190:191], v132 offset:0x3e00
	s_waitcnt lgkmcnt(6)
	v_mfma_f32_32x32x16_bf16 v[0:15], v[148:151], v[112:115], v[0:15]
	v_max_f32_e32 v112, v80, v81
	v_max3_f32 v112, v112, v82, v83
	v_max3_f32 v112, v112, v84, v85
	v_max3_f32 v112, v112, v86, v87
	v_max3_f32 v112, v112, v88, v89
	v_max3_f32 v112, v112, v90, v91
	v_max3_f32 v112, v112, v92, v93
	s_waitcnt lgkmcnt(4)
	v_mfma_f32_32x32x16_bf16 v[0:15], v[152:155], v[120:123], v[0:15]
	v_max3_f32 v112, v112, v94, v95
	v_max3_f32 v112, v112, v64, v65
	v_max3_f32 v112, v112, v66, v67
	v_max3_f32 v112, v112, v68, v69
	v_max3_f32 v112, v112, v70, v71
	v_max3_f32 v112, v112, v72, v73
	v_max3_f32 v112, v112, v74, v75
	v_max3_f32 v112, v112, v76, v77
	s_waitcnt lgkmcnt(2)
	v_mfma_f32_32x32x16_bf16 v[0:15], v[170:173], v[124:127], v[0:15]
	v_max3_f32 v112, v112, v78, v79
	v_mov_b32_e32 v113, v112
	s_nop 1
	v_permlane32_swap_b32_e32 v112, v113
	v_max_f32_e32 v112, v112, v113
	v_cmp_ge_f32_e32 vcc, s70, v112
	s_waitcnt lgkmcnt(0)
	v_mfma_f32_32x32x16_bf16 v[0:15], v[188:191], v[144:147], v[0:15]
	s_cmp_eq_u64 vcc, exec
	s_cselect_b64 s[4:5], -1, 0
	s_waitcnt vmcnt(0) lgkmcnt(0)
	s_barrier
	s_cbranch_scc1 .Lal_c_d1
	v_max_f32_e32 v242, 0, v112
	v_exp_f32_e64 v116, -v242
	s_nop 0
	v_pk_mul_f32 v[46:47], v[46:47], v[116:117] op_sel_hi:[1,0]
	v_pk_mul_f32 v[44:45], v[44:45], v[116:117] op_sel_hi:[1,0]
	v_pk_mul_f32 v[42:43], v[42:43], v[116:117] op_sel_hi:[1,0]
	v_pk_mul_f32 v[40:41], v[40:41], v[116:117] op_sel_hi:[1,0]
	v_pk_mul_f32 v[38:39], v[38:39], v[116:117] op_sel_hi:[1,0]
	v_pk_mul_f32 v[36:37], v[36:37], v[116:117] op_sel_hi:[1,0]
	v_pk_mul_f32 v[34:35], v[34:35], v[116:117] op_sel_hi:[1,0]
	v_pk_mul_f32 v[32:33], v[32:33], v[116:117] op_sel_hi:[1,0]
	v_pk_mul_f32 v[62:63], v[62:63], v[116:117] op_sel_hi:[1,0]
	v_pk_mul_f32 v[60:61], v[60:61], v[116:117] op_sel_hi:[1,0]
	v_pk_mul_f32 v[58:59], v[58:59], v[116:117] op_sel_hi:[1,0]
	v_pk_mul_f32 v[56:57], v[56:57], v[116:117] op_sel_hi:[1,0]
	v_pk_mul_f32 v[54:55], v[54:55], v[116:117] op_sel_hi:[1,0]
	v_pk_mul_f32 v[52:53], v[52:53], v[116:117] op_sel_hi:[1,0]
	v_pk_mul_f32 v[50:51], v[50:51], v[116:117] op_sel_hi:[1,0]
	v_pk_mul_f32 v[48:49], v[48:49], v[116:117] op_sel_hi:[1,0]
	v_pk_mul_f32 v[30:31], v[30:31], v[116:117] op_sel_hi:[1,0]
	v_pk_mul_f32 v[28:29], v[28:29], v[116:117] op_sel_hi:[1,0]
	v_pk_mul_f32 v[26:27], v[26:27], v[116:117] op_sel_hi:[1,0]
	v_pk_mul_f32 v[24:25], v[24:25], v[116:117] op_sel_hi:[1,0]
	v_pk_mul_f32 v[22:23], v[22:23], v[116:117] op_sel_hi:[1,0]
	v_pk_mul_f32 v[20:21], v[20:21], v[116:117] op_sel_hi:[1,0]
	v_pk_mul_f32 v[18:19], v[18:19], v[116:117] op_sel_hi:[1,0]
	v_pk_mul_f32 v[16:17], v[16:17], v[116:117] op_sel_hi:[1,0]
	v_pk_mul_f32 v[14:15], v[14:15], v[116:117] op_sel_hi:[1,0]
	v_pk_mul_f32 v[12:13], v[12:13], v[116:117] op_sel_hi:[1,0]
	v_pk_mul_f32 v[10:11], v[10:11], v[116:117] op_sel_hi:[1,0]
	v_pk_mul_f32 v[8:9], v[8:9], v[116:117] op_sel_hi:[1,0]
	v_pk_mul_f32 v[6:7], v[6:7], v[116:117] op_sel_hi:[1,0]
	v_pk_mul_f32 v[4:5], v[4:5], v[116:117] op_sel_hi:[1,0]
	v_pk_mul_f32 v[2:3], v[2:3], v[116:117] op_sel_hi:[1,0]
	v_pk_mul_f32 v[0:1], v[0:1], v[116:117] op_sel_hi:[1,0]
	v_sub_f32_e32 v80, v80, v242
	v_sub_f32_e32 v81, v81, v242
	v_sub_f32_e32 v82, v82, v242
	v_sub_f32_e32 v83, v83, v242
	v_sub_f32_e32 v84, v84, v242
	v_sub_f32_e32 v85, v85, v242
	v_sub_f32_e32 v86, v86, v242
	v_sub_f32_e32 v87, v87, v242
	v_sub_f32_e32 v88, v88, v242
	v_sub_f32_e32 v89, v89, v242
	v_sub_f32_e32 v90, v90, v242
	v_sub_f32_e32 v91, v91, v242
	v_sub_f32_e32 v92, v92, v242
	v_sub_f32_e32 v93, v93, v242
	v_sub_f32_e32 v94, v94, v242
	v_sub_f32_e32 v95, v95, v242
	v_sub_f32_e32 v64, v64, v242
	v_sub_f32_e32 v65, v65, v242
	v_sub_f32_e32 v66, v66, v242
	v_sub_f32_e32 v67, v67, v242
	v_sub_f32_e32 v68, v68, v242
	v_sub_f32_e32 v69, v69, v242
	v_sub_f32_e32 v70, v70, v242
	v_sub_f32_e32 v71, v71, v242
	v_sub_f32_e32 v72, v72, v242
	v_sub_f32_e32 v73, v73, v242
	v_sub_f32_e32 v74, v74, v242
	v_sub_f32_e32 v75, v75, v242
	v_sub_f32_e32 v76, v76, v242
	v_sub_f32_e32 v77, v77, v242
	v_sub_f32_e32 v78, v78, v242
	v_sub_f32_e32 v79, v79, v242
	v_sub_f32_e32 v226, v226, v242
	v_sub_f32_e32 v227, v227, v242
	v_sub_f32_e32 v228, v228, v242
	v_sub_f32_e32 v229, v229, v242
	v_sub_f32_e32 v230, v230, v242
	v_sub_f32_e32 v231, v231, v242
	v_sub_f32_e32 v232, v232, v242
	v_sub_f32_e32 v233, v233, v242
	v_sub_f32_e32 v234, v234, v242
	v_sub_f32_e32 v235, v235, v242
	v_sub_f32_e32 v236, v236, v242
	v_sub_f32_e32 v237, v237, v242
	v_sub_f32_e32 v238, v238, v242
	v_sub_f32_e32 v239, v239, v242
	v_sub_f32_e32 v240, v240, v242
	v_sub_f32_e32 v241, v241, v242
	s_branch .LBB0_131

; __device__ __forceinline__ void finishSM(f32x16& p0, f32x16& p1, float alpha, float& l_reg, bf16x8& pa0, bf16x8& pa1, bf16x8& pa2, bf16x8& pa3) {
; #pragma unroll
;   for (int r = 0; r < 16; ++r) p1[r] = __builtin_amdgcn_exp2f(p1[r]);
;   float ps = 0;
; #pragma unroll
;   for (int r = 0; r < 16; ++r) ps += p0[r];
; #pragma unroll
;   for (int r = 0; r < 16; ++r) ps += p1[r];
;   { auto rr = __builtin_amdgcn_permlane32_swap(__float_as_uint(ps), __float_as_uint(ps), false, false);
;     ps = __uint_as_float(rr[0]) + __uint_as_float(rr[1]); }
;   l_reg = l_reg * alpha + ps;
;     ...
;   PK4(p0, 0, pa0); PK4(p0, 8, pa1); PK4(p1, 0, pa2); PK4(p1, 8, pa3);
; template <int BUFOFF>
; __device__ __forceinline__ void qkt_diff(f32x16& p0, f32x16& p1, const int* ka, const bf16x8* qr) {
;   typedef __attribute__((address_space(3))) const bf16x8* lp;
;   p0 = f32x16{}; p1 = f32x16{};
; #pragma unroll
;   for (int d0 = 0; d0 < 4; ++d0) {
;     const int a = ka[d0] + BUFOFF;
;     const bf16x8 b0 = *(lp)(a), b1 = *(lp)(a + 8192);
;     p0 = __builtin_amdgcn_mfma_f32_32x32x16_bf16(b0, qr[d0], p0, 0, 0, 0);
;     p1 = __builtin_amdgcn_mfma_f32_32x32x16_bf16(b1, qr[d0], p1, 0, 0, 0);
;   }
; }
.LBB0_131:
	v_exp_f32_e32 v125, v64
	v_exp_f32_e32 v126, v65
	v_exp_f32_e32 v127, v66
	v_exp_f32_e32 v128, v67
	v_exp_f32_e32 v129, v68
	v_exp_f32_e32 v143, v69
	v_exp_f32_e32 v144, v70
	v_exp_f32_e32 v145, v71
	v_exp_f32_e32 v146, v72
	v_exp_f32_e32 v147, v73
	v_exp_f32_e32 v148, v74
	v_exp_f32_e32 v149, v75
	v_exp_f32_e32 v150, v76
	v_exp_f32_e32 v151, v80
	v_exp_f32_e32 v152, v81
	v_exp_f32_e32 v153, v82
	v_exp_f32_e32 v154, v83
	v_exp_f32_e32 v155, v84
	v_exp_f32_e32 v156, v85
	v_exp_f32_e32 v158, v86
	v_exp_f32_e32 v159, v87
	v_exp_f32_e32 v162, v88
	v_exp_f32_e32 v167, v89
	v_exp_f32_e32 v169, v90
	v_exp_f32_e32 v170, v91
	v_exp_f32_e32 v171, v92
	v_exp_f32_e32 v172, v93
	v_exp_f32_e32 v173, v94
	v_exp_f32_e32 v188, v95
	v_exp_f32_e32 v189, v77
	v_exp_f32_e32 v190, v78
	v_exp_f32_e32 v124, v79
	ds_read_b128 v[64:67], v138
	ds_read_b128 v[68:71], v138 offset:8192
	ds_read_b128 v[112:115], v141
	ds_read_b128 v[120:123], v141 offset:8192
	v_mov_b32_e32 v191, v125
	s_waitcnt lgkmcnt(0)
	v_mfma_f32_32x32x16_bf16 v[80:95], v[64:67], v[108:111], v[226:241]
	v_mfma_f32_32x32x16_bf16 v[64:79], v[68:71], v[108:111], v[226:241]
	v_mov_b32_e32 v192, v124
	v_mfma_f32_32x32x16_bf16 v[80:95], v[112:115], v[104:107], v[80:95]
	v_mfma_f32_32x32x16_bf16 v[64:79], v[120:123], v[104:107], v[64:79]
	ds_read_b128 v[112:115], v140
	ds_read_b128 v[120:123], v140 offset:8192
	s_waitcnt lgkmcnt(0)
	v_mfma_f32_32x32x16_bf16 v[80:95], v[112:115], v[100:103], v[80:95]
	v_mfma_f32_32x32x16_bf16 v[64:79], v[120:123], v[100:103], v[64:79]
	ds_read_b128 v[112:115], v139
	ds_read_b128 v[120:123], v139 offset:8192
	s_waitcnt lgkmcnt(0)
	v_mfma_f32_32x32x16_bf16 v[80:95], v[112:115], v[96:99], v[80:95]
	v_add_f32_e32 v112, v162, v151
	v_add_f32_e32 v243, v167, v152
	v_add_f32_e32 v244, v169, v153
	v_add_f32_e32 v245, v170, v154
	v_add_f32_e32 v246, v171, v155
	v_add_f32_e32 v247, v172, v156
	v_add_f32_e32 v251, v173, v158
	v_add_f32_e32 v252, v188, v159
	v_add_f32_e32 v112, v191, v112
	v_add_f32_e32 v243, v126, v243
	v_add_f32_e32 v244, v127, v244
	v_add_f32_e32 v245, v128, v245
	v_add_f32_e32 v246, v129, v246
	v_add_f32_e32 v247, v143, v247
	v_add_f32_e32 v251, v144, v251
	v_add_f32_e32 v252, v145, v252
	v_add_f32_e32 v112, v146, v112
	v_add_f32_e32 v243, v147, v243
	v_mfma_f32_32x32x16_bf16 v[64:79], v[120:123], v[96:99], v[64:79]
	v_add_f32_e32 v244, v148, v244
	v_add_f32_e32 v245, v149, v245
	v_add_f32_e32 v246, v150, v246
	v_add_f32_e32 v247, v189, v247
	v_add_f32_e32 v251, v190, v251
	v_add_f32_e32 v252, v192, v252
	v_add_f32_e32 v112, v112, v243
	v_add_f32_e32 v244, v244, v245
	v_add_f32_e32 v246, v246, v247
	v_add_f32_e32 v251, v251, v252
	v_add_f32_e32 v112, v112, v244
	v_add_f32_e32 v246, v246, v251
	v_add_f32_e32 v120, v112, v246
	v_mov_b32_e32 v121, v120
	v_cvt_pk_bf16_f32 v112, v151, v152
	v_cvt_pk_bf16_f32 v113, v153, v154
	v_cvt_pk_bf16_f32 v114, v155, v156
	v_cvt_pk_bf16_f32 v115, v158, v159
	s_nop 1
	v_permlane32_swap_b32_e32 v120, v121
	v_cvt_pk_bf16_f32 v122, v162, v167
	v_cvt_pk_bf16_f32 v123, v169, v170
	v_cvt_pk_bf16_f32 v124, v171, v172
	v_cvt_pk_bf16_f32 v125, v173, v188
	v_cvt_pk_bf16_f32 v126, v191, v126
	v_cvt_pk_bf16_f32 v127, v127, v128
	v_cvt_pk_bf16_f32 v128, v129, v143
	v_cvt_pk_bf16_f32 v129, v144, v145
	v_cvt_pk_bf16_f32 v144, v146, v147
	v_cvt_pk_bf16_f32 v145, v148, v149
	v_cvt_pk_bf16_f32 v146, v150, v189
	v_cvt_pk_bf16_f32 v147, v190, v192
	s_nop 0
	s_add_u32 s4, s14, 0x20000
	s_addc_u32 s5, s15, 0
	s_add_u32 s56, s14, 0x2020000
	s_mov_b32 m0, s16
	s_addc_u32 s57, s15, 0
	s_add_i32 s55, s42, s55
	s_nop 0
	global_load_lds_dwordx4 v134, s[4:5]
	s_mov_b32 m0, s17
	s_nop 0
	global_load_lds_dwordx4 v135, s[4:5]
	s_mov_b32 m0, s55
	s_nop 0
	global_load_lds_dwordx4 v136, s[56:57]
	s_add_i32 m0, s55, 0x2000
	s_nop 0
	global_load_lds_dwordx4 v137, s[56:57]
	v_lshl_add_u32 v143, s54, 14, v133
	ds_read_b64_tr_b16 v[148:149], v143 offset:0
	ds_read_b64_tr_b16 v[150:151], v143 offset:0x800
	ds_read_b64_tr_b16 v[152:153], v143 offset:0x1000
	ds_read_b64_tr_b16 v[154:155], v143 offset:0x1800
	ds_read_b64_tr_b16 v[170:171], v143 offset:0x2000
	ds_read_b64_tr_b16 v[172:173], v143 offset:0x2800
	ds_read_b64_tr_b16 v[188:189], v143 offset:0x3000
	ds_read_b64_tr_b16 v[190:191], v143 offset:0x3800
	s_nop 0
	s_waitcnt lgkmcnt(6)
	v_mfma_f32_32x32x16_bf16 v[32:47], v[148:151], v[112:115], v[32:47]
	ds_read_b64_tr_b16 v[148:149], v143 offset:0x200
	ds_read_b64_tr_b16 v[150:151], v143 offset:0xa00
	s_waitcnt lgkmcnt(6)
	v_mfma_f32_32x32x16_bf16 v[32:47], v[152:155], v[122:125], v[32:47]
	ds_read_b64_tr_b16 v[152:153], v143 offset:0x1200
	ds_read_b64_tr_b16 v[154:155], v143 offset:0x1a00
	s_waitcnt lgkmcnt(6)
	v_mfma_f32_32x32x16_bf16 v[32:47], v[170:173], v[126:129], v[32:47]
	ds_read_b64_tr_b16 v[170:171], v143 offset:0x2200
	ds_read_b64_tr_b16 v[172:173], v143 offset:0x2a00
	s_waitcnt lgkmcnt(6)
	v_mfma_f32_32x32x16_bf16 v[32:47], v[188:191], v[144:147], v[32:47]
	ds_read_b64_tr_b16 v[188:189], v143 offset:0x3200
	ds_read_b64_tr_b16 v[190:191], v143 offset:0x3a00
	s_waitcnt lgkmcnt(6)
	v_mfma_f32_32x32x16_bf16 v[48:63], v[148:151], v[112:115], v[48:63]
	ds_read_b64_tr_b16 v[148:149], v143 offset:0x400
	ds_read_b64_tr_b16 v[150:151], v143 offset:0xc00
	s_waitcnt lgkmcnt(6)
	v_mfma_f32_32x32x16_bf16 v[48:63], v[152:155], v[122:125], v[48:63]
	ds_read_b64_tr_b16 v[152:153], v143 offset:0x1400
	ds_read_b64_tr_b16 v[154:155], v143 offset:0x1c00
	s_waitcnt lgkmcnt(6)
	v_mfma_f32_32x32x16_bf16 v[48:63], v[170:173], v[126:129], v[48:63]
	ds_read_b64_tr_b16 v[170:171], v143 offset:0x2400
	ds_read_b64_tr_b16 v[172:173], v143 offset:0x2c00
	s_waitcnt lgkmcnt(6)
; #define SBAR() __builtin_amdgcn_sched_barrier(0)
; template <int MLA>
; __device__ __forceinline__ void partialSM(f32x16& p0, f32x16& p1, float& m_reg, float& mn, float& alpha) {
;     ...
;   float pmax = p0[0];
; #pragma unroll
;   for (int r = 1; r < 16; ++r) pmax = fmaxf(pmax, p0[r]);
; #pragma unroll
;   for (int r = 0; r < 16; ++r) pmax = fmaxf(pmax, p1[r]);
;   { auto rr = __builtin_amdgcn_permlane32_swap(__float_as_uint(pmax), __float_as_uint(pmax), false, false);
;     pmax = fmaxf(__uint_as_float(rr[0]), __uint_as_float(rr[1])); }
;   if (__builtin_expect(__all(pmax - m_reg <= THR / SCALE), 1)) { mn = m_reg; alpha = 1.f; }
;   else { mn = fmaxf(m_reg, pmax); alpha = __builtin_amdgcn_exp2f((m_reg - mn) * C); m_reg = mn; }
; template <int D0> __device__ __forceinline__ void pv_one_t(f32x16& od, int vb, bf16x8 pa0, bf16x8 pa1, bf16x8 pa2, bf16x8 pa3) {
;   const s16x4 l0 = tr_read<v_rd_off(D0, 0, 0)>(vb), h0 = tr_read<v_rd_off(D0, 0, 1)>(vb), l1 = tr_read<v_rd_off(D0, 1, 0)>(vb), h1 = tr_read<v_rd_off(D0, 1, 1)>(vb);
;   const s16x4 l2 = tr_read<v_rd_off(D0, 2, 0)>(vb), h2 = tr_read<v_rd_off(D0, 2, 1)>(vb), l3 = tr_read<v_rd_off(D0, 3, 0)>(vb), h3 = tr_read<v_rd_off(D0, 3, 1)>(vb);
;   asm volatile("s_waitcnt lgkmcnt(0)" ::: "memory"); SBAR();
;     ...
;   od = __builtin_amdgcn_mfma_f32_32x32x16_bf16(PK(l0, h0), pa0, od, 0, 0, 0);
;   od = __builtin_amdgcn_mfma_f32_32x32x16_bf16(PK(l1, h1), pa1, od, 0, 0, 0);
;   od = __builtin_amdgcn_mfma_f32_32x32x16_bf16(PK(l2, h2), pa2, od, 0, 0, 0);
;   od = __builtin_amdgcn_mfma_f32_32x32x16_bf16(PK(l3, h3), pa3, od, 0, 0, 0);
;     ...
; }
	v_mfma_f32_32x32x16_bf16 v[48:63], v[188:191], v[144:147], v[48:63]
	ds_read_b64_tr_b16 v[188:189], v143 offset:0x3400
	ds_read_b64_tr_b16 v[190:191], v143 offset:0x3c00
	s_waitcnt lgkmcnt(6)
	v_mfma_f32_32x32x16_bf16 v[16:31], v[148:151], v[112:115], v[16:31]
	ds_read_b64_tr_b16 v[148:149], v143 offset:0x600
	ds_read_b64_tr_b16 v[150:151], v143 offset:0xe00
	s_waitcnt lgkmcnt(6)
	v_mfma_f32_32x32x16_bf16 v[16:31], v[152:155], v[122:125], v[16:31]
	ds_read_b64_tr_b16 v[152:153], v143 offset:0x1600
	ds_read_b64_tr_b16 v[154:155], v143 offset:0x1e00
	s_waitcnt lgkmcnt(6)
	v_mfma_f32_32x32x16_bf16 v[16:31], v[170:173], v[126:129], v[16:31]
	ds_read_b64_tr_b16 v[170:171], v143 offset:0x2600
	ds_read_b64_tr_b16 v[172:173], v143 offset:0x2e00
	s_waitcnt lgkmcnt(6)
	v_mfma_f32_32x32x16_bf16 v[16:31], v[188:191], v[144:147], v[16:31]
	ds_read_b64_tr_b16 v[188:189], v143 offset:0x3600
	ds_read_b64_tr_b16 v[190:191], v143 offset:0x3e00
	s_waitcnt lgkmcnt(6)
	v_mfma_f32_32x32x16_bf16 v[0:15], v[148:151], v[112:115], v[0:15]
	v_max_f32_e32 v112, v80, v81
	v_max3_f32 v112, v112, v82, v83
	v_max3_f32 v112, v112, v84, v85
	v_max3_f32 v112, v112, v86, v87
	v_max3_f32 v112, v112, v88, v89
	v_max3_f32 v112, v112, v90, v91
	v_max3_f32 v112, v112, v92, v93
	s_waitcnt lgkmcnt(4)
	v_mfma_f32_32x32x16_bf16 v[0:15], v[152:155], v[122:125], v[0:15]
	v_max3_f32 v112, v112, v94, v95
	v_max3_f32 v112, v112, v64, v65
	v_max3_f32 v112, v112, v66, v67
	v_max3_f32 v112, v112, v68, v69
	v_max3_f32 v112, v112, v70, v71
	v_max3_f32 v112, v112, v72, v73
	v_max3_f32 v112, v112, v74, v75
	v_max3_f32 v112, v112, v76, v77
	s_waitcnt lgkmcnt(2)
	v_mfma_f32_32x32x16_bf16 v[0:15], v[170:173], v[126:129], v[0:15]
	v_max3_f32 v112, v112, v78, v79
	v_mov_b32_e32 v113, v112
	s_nop 1
	v_permlane32_swap_b32_e32 v112, v113
	v_max_f32_e32 v112, v112, v113
	v_cmp_ge_f32_e32 vcc, s70, v112
	s_waitcnt lgkmcnt(0)
	v_mfma_f32_32x32x16_bf16 v[0:15], v[188:191], v[144:147], v[0:15]
	s_cmp_eq_u64 vcc, exec
	s_cselect_b64 s[4:5], -1, 0
	s_waitcnt vmcnt(0) lgkmcnt(0)
	s_barrier
	s_cbranch_scc1 .Lal_c_d2
	v_max_f32_e32 v242, 0, v112
	v_exp_f32_e64 v112, -v242
	s_nop 0
	v_pk_mul_f32 v[46:47], v[46:47], v[112:113] op_sel_hi:[1,0]
	v_pk_mul_f32 v[44:45], v[44:45], v[112:113] op_sel_hi:[1,0]
	v_pk_mul_f32 v[42:43], v[42:43], v[112:113] op_sel_hi:[1,0]
	v_pk_mul_f32 v[40:41], v[40:41], v[112:113] op_sel_hi:[1,0]
	v_pk_mul_f32 v[38:39], v[38:39], v[112:113] op_sel_hi:[1,0]
	v_pk_mul_f32 v[36:37], v[36:37], v[112:113] op_sel_hi:[1,0]
	v_pk_mul_f32 v[34:35], v[34:35], v[112:113] op_sel_hi:[1,0]
	v_pk_mul_f32 v[32:33], v[32:33], v[112:113] op_sel_hi:[1,0]
	v_pk_mul_f32 v[62:63], v[62:63], v[112:113] op_sel_hi:[1,0]
	v_pk_mul_f32 v[60:61], v[60:61], v[112:113] op_sel_hi:[1,0]
	v_pk_mul_f32 v[58:59], v[58:59], v[112:113] op_sel_hi:[1,0]
	v_pk_mul_f32 v[56:57], v[56:57], v[112:113] op_sel_hi:[1,0]
	v_pk_mul_f32 v[54:55], v[54:55], v[112:113] op_sel_hi:[1,0]
	v_pk_mul_f32 v[52:53], v[52:53], v[112:113] op_sel_hi:[1,0]
	v_pk_mul_f32 v[50:51], v[50:51], v[112:113] op_sel_hi:[1,0]
	v_pk_mul_f32 v[48:49], v[48:49], v[112:113] op_sel_hi:[1,0]
	v_pk_mul_f32 v[30:31], v[30:31], v[112:113] op_sel_hi:[1,0]
	v_pk_mul_f32 v[28:29], v[28:29], v[112:113] op_sel_hi:[1,0]
	v_pk_mul_f32 v[26:27], v[26:27], v[112:113] op_sel_hi:[1,0]
	v_pk_mul_f32 v[24:25], v[24:25], v[112:113] op_sel_hi:[1,0]
	v_pk_mul_f32 v[22:23], v[22:23], v[112:113] op_sel_hi:[1,0]
	v_pk_mul_f32 v[20:21], v[20:21], v[112:113] op_sel_hi:[1,0]
	v_pk_mul_f32 v[18:19], v[18:19], v[112:113] op_sel_hi:[1,0]
	v_pk_mul_f32 v[16:17], v[16:17], v[112:113] op_sel_hi:[1,0]
	v_pk_mul_f32 v[14:15], v[14:15], v[112:113] op_sel_hi:[1,0]
	v_pk_mul_f32 v[12:13], v[12:13], v[112:113] op_sel_hi:[1,0]
	v_pk_mul_f32 v[10:11], v[10:11], v[112:113] op_sel_hi:[1,0]
	v_pk_mul_f32 v[8:9], v[8:9], v[112:113] op_sel_hi:[1,0]
	v_pk_mul_f32 v[6:7], v[6:7], v[112:113] op_sel_hi:[1,0]
	v_pk_mul_f32 v[4:5], v[4:5], v[112:113] op_sel_hi:[1,0]
	v_pk_mul_f32 v[2:3], v[2:3], v[112:113] op_sel_hi:[1,0]
	v_pk_mul_f32 v[0:1], v[0:1], v[112:113] op_sel_hi:[1,0]
	v_sub_f32_e32 v80, v80, v242
	v_sub_f32_e32 v81, v81, v242
	v_sub_f32_e32 v82, v82, v242
	v_sub_f32_e32 v83, v83, v242
	v_sub_f32_e32 v84, v84, v242
	v_sub_f32_e32 v85, v85, v242
	v_sub_f32_e32 v86, v86, v242
	v_sub_f32_e32 v87, v87, v242
	v_sub_f32_e32 v88, v88, v242
	v_sub_f32_e32 v89, v89, v242
	v_sub_f32_e32 v90, v90, v242
	v_sub_f32_e32 v91, v91, v242
	v_sub_f32_e32 v92, v92, v242
	v_sub_f32_e32 v93, v93, v242
	v_sub_f32_e32 v94, v94, v242
	v_sub_f32_e32 v95, v95, v242
	v_sub_f32_e32 v64, v64, v242
	v_sub_f32_e32 v65, v65, v242
	v_sub_f32_e32 v66, v66, v242
	v_sub_f32_e32 v67, v67, v242
	v_sub_f32_e32 v68, v68, v242
	v_sub_f32_e32 v69, v69, v242
	v_sub_f32_e32 v70, v70, v242
	v_sub_f32_e32 v71, v71, v242
	v_sub_f32_e32 v72, v72, v242
	v_sub_f32_e32 v73, v73, v242
	v_sub_f32_e32 v74, v74, v242
	v_sub_f32_e32 v75, v75, v242
	v_sub_f32_e32 v76, v76, v242
	v_sub_f32_e32 v77, v77, v242
	v_sub_f32_e32 v78, v78, v242
	v_sub_f32_e32 v79, v79, v242
	v_sub_f32_e32 v226, v226, v242
	v_sub_f32_e32 v227, v227, v242
	v_sub_f32_e32 v228, v228, v242
	v_sub_f32_e32 v229, v229, v242
	v_sub_f32_e32 v230, v230, v242
	v_sub_f32_e32 v231, v231, v242
	v_sub_f32_e32 v232, v232, v242
	v_sub_f32_e32 v233, v233, v242
	v_sub_f32_e32 v234, v234, v242
	v_sub_f32_e32 v235, v235, v242
	v_sub_f32_e32 v236, v236, v242
	v_sub_f32_e32 v237, v237, v242
	v_sub_f32_e32 v238, v238, v242
	v_sub_f32_e32 v239, v239, v242
	v_sub_f32_e32 v240, v240, v242
	v_sub_f32_e32 v241, v241, v242
	s_branch .LBB0_133
